# scan1 tail: statically assigned first chunk for the workgroups with two gates units (no dequeue atomic at tail entry)
# baseline (speedup 1.0000x reference)
.LBB0_468:
	s_add_u32 s4, s24, 0x74100
	s_addc_u32 s5, s25, 0
	s_add_u32 s3, s24, 0x6c000
	s_addc_u32 s16, s25, 0
	s_add_u32 s14, s24, 0x3400000
	s_addc_u32 s15, s25, 0
	s_add_i32 s17, 0, 0x20080
	s_mov_b32 s43, 0
	v_mov_b32_e32 v41, 0
	s_movk_i32 s27, 0x407f
	s_mov_b32 s28, 0xfe03f81
	s_mov_b32 s29, 0x1fc07f
	v_mov_b32_e32 v44, s17
	s_cmp_gt_u32 s101, 23
	s_cselect_b32 s100, 1, 0
	s_sub_u32 s98, s101, 24
	s_mov_b32 s99, 0
	s_branch .LBB0_472

.LBB0_472:
	s_barrier
	s_and_saveexec_b64 s[0:1], s[92:93]
	s_cbranch_execz .LBB0_506
	s_mov_b64 s[38:39], exec
	v_mbcnt_lo_u32_b32 v0, s38, 0
	v_mbcnt_hi_u32_b32 v0, s39, v0
	v_cmp_eq_u32_e32 vcc, 0, v0
	s_and_saveexec_b64 s[36:37], vcc
	s_cbranch_execz .LBB0_475
	s_bcnt1_i32_b64 s8, s[38:39]
	s_cmp_eq_u32 s100, 1
	s_cbranch_scc1 .Lsf1_st
	v_mov_b32_e32 v1, s8
	global_atomic_add v1, v41, v1, s[4:5] sc0
	s_waitcnt vmcnt(0)
	v_add_u32_e32 v1, 0xe8, v1
	s_branch .Lsf1_dn
.Lsf1_st:
	v_mov_b32_e32 v1, s98
	s_mov_b32 s100, 0
.Lsf1_dn:
.LBB0_475:
	s_or_b64 exec, exec, s[36:37]
	s_waitcnt vmcnt(0)
	v_readfirstlane_b32 s8, v1
	s_nop 1
	v_add_u32_e32 v2, s8, v0
	s_movk_i32 s8, 0x214
	v_cmp_gt_u32_e32 vcc, s8, v2
	s_and_saveexec_b64 s[36:37], vcc
	s_cbranch_execz .LBB0_505
	v_lshlrev_b32_e32 v0, 5, v2
	v_and_b32_e32 v40, 0x7f00, v0
	v_lshl_add_u64 v[0:1], s[10:11], 0, v[40:41]
	s_mov_b32 s18, 0x40001
	s_mov_b64 s[38:39], 0
	s_branch .LBB0_490
